# v62 + SB: canonicalising v_max merged (31), next-tile loads in saddr form
# speedup vs baseline: 1.0078x; 1.0007x over previous
.LBB0_585:
	s_and_b32 s4, s63, 7
	s_lshl_b32 s5, s4, 2
	v_mov_b32_e32 v6, v225
	s_or_b32 s71, s5, 2
	s_and_b32 s42, s3, 7
	v_readfirstlane_b32 s5, v6
	s_ashr_i32 s64, s5, 6
	s_lshl_b32 s65, s4, 8
	s_ashr_i32 s4, s3, 6
	s_lshl_b32 s5, s42, 8
	s_lshl_b32 s66, s64, 5
	s_add_i32 s66, s66, s5
	s_ashr_i32 s5, s4, 31
	s_bfe_u32 s8, s3, 0x30003
	v_and_b32_e32 v7, 31, v6
	s_lshl_b64 s[38:39], s[4:5], 11
	s_lshl_b32 s4, s4, 3
	s_waitcnt vmcnt(2)
	v_or_b32_e32 v150, s66, v7
	s_or_b32 s4, s4, s8
	s_ashr_i32 s5, s4, 31
	v_ashrrev_i32_e32 v151, 31, v150
	s_lshl_b64 s[4:5], s[4:5], 19
	v_lshl_add_u64 v[2:3], s[38:39], 0, v[150:151]
	s_add_u32 s6, s14, s4
	v_mad_u64_u32 v[4:5], s[40:41], v2, s44, v[146:147]
	v_bfe_u32 v8, v6, 5, 1
	s_addc_u32 s7, s15, s5
	v_mad_i32_i24 v5, v3, s44, v5
	s_lshl_b32 s67, s8, 7
	s_lshl_b32 s8, s8, 8
	v_lshl_add_u64 v[2:3], v[4:5], 0, s[8:9]
	v_lshlrev_b32_e32 v0, 4, v8
	v_lshl_add_u64 v[2:3], v[2:3], 0, v[0:1]
	global_load_dwordx4 v[98:101], v[2:3], off
	global_load_dwordx4 v[102:105], v[2:3], off offset:32
	global_load_dwordx4 v[106:109], v[2:3], off offset:64
	global_load_dwordx4 v[110:113], v[2:3], off offset:96
	global_load_dwordx4 v[114:117], v[2:3], off offset:128
	global_load_dwordx4 v[118:121], v[2:3], off offset:160
	global_load_dwordx4 v[122:125], v[2:3], off offset:192
	global_load_dwordx4 v[126:129], v[2:3], off offset:224
	v_lshlrev_b32_e32 v2, 3, v6
	s_add_u32 s4, s81, s4
	v_ashrrev_i32_e32 v3, 31, v2
	s_addc_u32 s5, s82, s5
	v_lshlrev_b64 v[2:3], 1, v[2:3]
	v_mov_b32_e32 v228, v2
	v_add_u32_e32 v229, 0x2000, v2
	s_waitcnt vmcnt(9)
	s_mov_b64 s[90:91], s[4:5]
	v_lshl_add_u64 v[154:155], s[4:5], 0, v[2:3]
	s_lshl_b32 s4, s42, 16
	s_mov_b64 s[88:89], s[6:7]
	v_lshl_add_u64 v[152:153], s[6:7], 0, v[2:3]
	s_or_b32 s8, s4, 0xc000
	v_lshl_add_u64 v[2:3], v[152:153], 0, s[8:9]
	s_barrier
	v_lshl_add_u64 v[4:5], v[154:155], 0, s[8:9]
	global_load_dwordx4 v[130:133], v[2:3], off
	global_load_dwordx4 v[134:137], v[4:5], off
	v_add_co_u32_e32 v2, vcc, s46, v2
	v_and_b32_e32 v149, 63, v6
	s_nop 0
	v_addc_co_u32_e32 v3, vcc, 0, v3, vcc
	v_add_co_u32_e32 v4, vcc, s46, v4
	v_mul_u32_u24_e32 v197, 0x110, v7
	s_nop 0
	v_addc_co_u32_e32 v5, vcc, 0, v5, vcc
	global_load_dwordx4 v[138:141], v[2:3], off
	global_load_dwordx4 v[142:145], v[4:5], off
	v_lshlrev_b32_e32 v2, 4, v6
	v_lshrrev_b32_e32 v3, 3, v6
	v_lshrrev_b32_e32 v4, 4, v6
	v_and_b32_e32 v148, 0xf0, v2
	v_and_b32_e32 v2, 0x70, v2
	s_waitcnt vmcnt(12)
	v_mad_u64_u32 v[156:157], s[4:5], v4, s47, v[148:149]
	v_mad_u64_u32 v[158:159], s[4:5], v3, s48, v[2:3]
	v_lshlrev_b32_e32 v5, 7, v7
	v_add3_u32 v157, 0, v197, v0
	v_add_u32_e32 v0, 0, v156
	v_add_u32_e32 v2, 0, v158
	v_mov_b32_e32 v14, v1
	v_mov_b32_e32 v15, v1
	v_lshlrev_b32_e32 v151, 3, v8
	s_lshl_b32 s4, s64, 2
	v_lshlrev_b32_e32 v159, 2, v8
	v_sub_u32_e32 v198, v157, v5
	v_mov_b32_e32 v3, v1
	v_mov_b32_e32 v4, v1
	v_mov_b32_e32 v5, v1
	v_mov_b32_e32 v6, v1
	v_mov_b32_e32 v7, v1
	v_mov_b32_e32 v8, v1
	v_mov_b32_e32 v9, v1
	v_mov_b32_e32 v10, v1
	v_mov_b32_e32 v11, v1
	v_mov_b32_e32 v12, v1
	v_mov_b32_e32 v13, v1
	s_add_i32 s69, s4, 0
	v_cmp_eq_u32_e64 s[6:7], 0, v149
	s_or_b32 s68, s66, 30
	s_add_i32 s69, s69, 0x11800
	v_cmp_gt_u32_e64 s[4:5], 32, v149
	s_mov_b64 s[42:43], 0
	s_mov_b32 s70, s9
	s_mov_b32 s8, s71
	s_mov_b32 s71, s9
	s_waitcnt vmcnt(3)
	ds_write_b128 v0, v[130:133]
	s_waitcnt vmcnt(2)
	ds_write_b128 v2, v[134:137] offset:17408
	s_waitcnt vmcnt(1)
	ds_write_b128 v0, v[138:141] offset:8704
	s_waitcnt vmcnt(0)
	ds_write_b128 v2, v[142:145] offset:26624
	v_mov_b32_e32 v0, v1
	v_mov_b32_e32 v2, v1
	v_mov_b64_e32 v[64:65], v[14:15]
	v_mov_b64_e32 v[48:49], v[14:15]
	v_mov_b64_e32 v[32:33], v[14:15]
	v_mov_b64_e32 v[62:63], v[12:13]
	v_mov_b64_e32 v[60:61], v[10:11]
	v_mov_b64_e32 v[58:59], v[8:9]
	v_mov_b64_e32 v[56:57], v[6:7]
	v_mov_b64_e32 v[54:55], v[4:5]
	v_mov_b64_e32 v[52:53], v[2:3]
	v_mov_b64_e32 v[50:51], v[0:1]
	v_mov_b64_e32 v[46:47], v[12:13]
	v_mov_b64_e32 v[44:45], v[10:11]
	v_mov_b64_e32 v[42:43], v[8:9]
	v_mov_b64_e32 v[40:41], v[6:7]
	v_mov_b64_e32 v[38:39], v[4:5]
	v_mov_b64_e32 v[36:37], v[2:3]
	v_mov_b64_e32 v[34:35], v[0:1]
	v_mov_b64_e32 v[30:31], v[12:13]
	v_mov_b64_e32 v[28:29], v[10:11]
	v_mov_b64_e32 v[26:27], v[8:9]
	v_mov_b64_e32 v[24:25], v[6:7]
	v_mov_b64_e32 v[22:23], v[4:5]
	v_mov_b64_e32 v[20:21], v[2:3]
	v_mov_b64_e32 v[18:19], v[0:1]
	v_mov_b64_e32 v[16:17], v[14:15]
	v_mov_b64_e32 v[14:15], v[12:13]
	v_mov_b64_e32 v[12:13], v[10:11]
	v_mov_b64_e32 v[10:11], v[8:9]
	v_mov_b64_e32 v[8:9], v[6:7]
	v_mov_b64_e32 v[6:7], v[4:5]
	v_mov_b64_e32 v[4:5], v[2:3]
	v_mov_b64_e32 v[2:3], v[0:1]
	v_mov_b32_e32 v0, 0
	s_waitcnt lgkmcnt(0)
	s_barrier
	s_branch .LBB0_587

.LBB0_587:
	s_add_i32 s72, s8, 1
	s_cmp_gt_i32 s72, 0
	s_cselect_b64 s[40:41], -1, 0
	s_cmp_lt_i32 s72, 1
	s_cbranch_scc1 .LBB0_589
	s_lshl_b64 s[72:73], s[8:9], 14
	s_add_u32 s92, s88, s72
	s_addc_u32 s93, s89, s73
	s_add_u32 s94, s90, s72
	s_addc_u32 s95, s91, s73
	global_load_dwordx4 v[130:133], v228, s[92:93]
	global_load_dwordx4 v[134:137], v228, s[94:95]
	global_load_dwordx4 v[138:141], v229, s[92:93]
	global_load_dwordx4 v[142:145], v229, s[94:95]
.LBB0_589:
	s_add_i32 s72, s65, 0xc0
	s_cmp_gt_i32 s72, s68
	s_cselect_b64 s[72:73], -1, 0
	s_or_b64 s[72:73], s[42:43], s[72:73]
	s_and_b64 vcc, exec, s[72:73]
	s_cbranch_vccnz .LBB0_594
	s_mul_i32 s42, s71, 0x8c00
	v_add_u32_e32 v188, s42, v157
	ds_read_b128 v[66:69], v188
	ds_read_b128 v[160:163], v188 offset:32
	ds_read_b128 v[82:85], v188 offset:8704
	ds_read_b128 v[164:167], v188 offset:8736
	v_add_u32_e32 v199, s65, v159
	v_add_u32_e32 v189, 0xe0, v199
	s_waitcnt lgkmcnt(1)
	v_mfma_f32_32x32x16_bf16 v[82:97], v[82:85], v[98:101], 0
	v_add_u32_e32 v190, 0xe1, v199
	v_cmp_lt_i32_e32 vcc, v189, v150
	v_add_u32_e32 v191, 0xe2, v199
	v_add_u32_e32 v192, 0xe3, v199
	v_add_u32_e32 v193, 0xe8, v199
	v_add_u32_e32 v204, 0xe9, v199
	v_add_u32_e32 v205, 0xea, v199
	s_waitcnt lgkmcnt(0)
	v_mfma_f32_32x32x16_bf16 v[82:97], v[164:167], v[102:105], v[82:97]
	ds_read_b128 v[164:167], v188 offset:8768
	ds_read_b128 v[168:171], v188 offset:8800
	v_add_u32_e32 v206, 0xeb, v199
	s_waitcnt lgkmcnt(1)
	v_mfma_f32_32x32x16_bf16 v[82:97], v[164:167], v[106:109], v[82:97]
	s_waitcnt lgkmcnt(0)
	v_mfma_f32_32x32x16_bf16 v[82:97], v[168:171], v[110:113], v[82:97]
	ds_read_b128 v[164:167], v188 offset:8832
	ds_read_b128 v[168:171], v188 offset:8864
	s_waitcnt lgkmcnt(1)
	v_mfma_f32_32x32x16_bf16 v[82:97], v[164:167], v[114:117], v[82:97]
	ds_read_b128 v[164:167], v188 offset:8896
	s_waitcnt lgkmcnt(1)
	v_mfma_f32_32x32x16_bf16 v[82:97], v[168:171], v[118:121], v[82:97]
	ds_read_b128 v[168:171], v188 offset:64
	ds_read_b128 v[172:175], v188 offset:96
	ds_read_b128 v[176:179], v188 offset:8928
	s_waitcnt lgkmcnt(3)
	v_mfma_f32_32x32x16_bf16 v[82:97], v[164:167], v[122:125], v[82:97]
	ds_read_b128 v[164:167], v188 offset:128
	ds_read_b128 v[180:183], v188 offset:160
	ds_read_b128 v[184:187], v188 offset:192
	ds_read_b128 v[200:203], v188 offset:224
	v_mfma_f32_32x32x16_bf16 v[66:81], v[66:69], v[98:101], 0
	s_waitcnt lgkmcnt(4)
	v_mfma_f32_32x32x16_bf16 v[82:97], v[176:179], v[126:129], v[82:97]
	v_mfma_f32_32x32x16_bf16 v[66:81], v[160:163], v[102:105], v[66:81]
	s_nop 10
	v_cndmask_b32_e32 v82, v194, v82, vcc
	v_cmp_lt_i32_e32 vcc, v190, v150
	v_exp_f32_e64 v176, -|v82|
	s_nop 0
	v_cndmask_b32_e32 v83, v194, v83, vcc
	v_cmp_lt_i32_e32 vcc, v191, v150
	v_exp_f32_e64 v177, -|v83|
	v_mfma_f32_32x32x16_bf16 v[66:81], v[168:171], v[106:109], v[66:81]
	v_cndmask_b32_e32 v84, v194, v84, vcc
	v_cmp_lt_i32_e32 vcc, v192, v150
	v_exp_f32_e64 v178, -|v84|
	v_pk_add_f32 v[160:161], v[176:177], 1.0 op_sel_hi:[1,0]
	v_cndmask_b32_e32 v85, v194, v85, vcc
	v_cmp_lt_i32_e32 vcc, v193, v150
	v_exp_f32_e64 v179, -|v85|
	v_log_f32_e32 v160, v160
	v_cndmask_b32_e32 v86, v194, v86, vcc
	v_cmp_lt_i32_e32 vcc, v204, v150
	v_exp_f32_e64 v188, -|v86|
	v_pk_add_f32 v[176:177], v[178:179], 1.0 op_sel_hi:[1,0]
	v_cndmask_b32_e32 v87, v194, v87, vcc
	v_exp_f32_e64 v189, -|v87|
	v_cmp_lt_i32_e32 vcc, v205, v150
	v_log_f32_e32 v161, v161
	v_log_f32_e32 v176, v176
	v_cndmask_b32_e32 v88, v194, v88, vcc
	v_cmp_lt_i32_e32 vcc, v206, v150
	v_pk_add_f32 v[178:179], v[188:189], 1.0 op_sel_hi:[1,0]
	v_exp_f32_e64 v190, -|v88|
	v_cndmask_b32_e32 v89, v194, v89, vcc
	v_exp_f32_e64 v191, -|v89|
	v_log_f32_e32 v177, v177
	v_log_f32_e32 v178, v178
	v_log_f32_e32 v179, v179
	v_max_f32_e32 v192, 0, v82
	v_max_f32_e32 v193, 0, v83
	v_max_f32_e32 v204, 0, v84
	v_max_f32_e32 v205, 0, v85
	v_max_f32_e32 v162, 0, v86
	v_max_f32_e32 v163, 0, v87
	v_mfma_f32_32x32x16_bf16 v[66:81], v[172:175], v[110:113], v[66:81]
	v_add_f32_e64 v188, v192, v160
	v_add_f32_e64 v189, v193, v161
	v_add_f32_e64 v160, v204, v176
	v_add_f32_e64 v161, v205, v177
	v_add_f32_e64 v176, v162, v178
	v_add_f32_e64 v177, v163, v179
	v_pk_add_f32 v[162:163], v[190:191], 1.0 op_sel_hi:[1,0]
	v_log_f32_e32 v168, v162
	v_max_f32_e32 v170, 0, v88
	v_add_u32_e32 v162, 0xf0, v199
	v_cmp_lt_i32_e32 vcc, v162, v150
	v_log_f32_e32 v169, v163
	s_waitcnt lgkmcnt(3)
	v_mfma_f32_32x32x16_bf16 v[66:81], v[164:167], v[114:117], v[66:81]
	v_cndmask_b32_e32 v162, v194, v90, vcc
	v_add_u32_e32 v90, 0xf1, v199
	v_cmp_lt_i32_e32 vcc, v90, v150
	v_exp_f32_e64 v90, -|v162|
	v_add_u32_e32 v167, 0xf2, v199
	v_cndmask_b32_e32 v163, v194, v91, vcc
	v_exp_f32_e64 v91, -|v163|
	v_max_f32_e32 v171, 0, v89
	v_cmp_lt_i32_e32 vcc, v167, v150
	v_pk_add_f32 v[164:165], v[170:171], v[168:169]
	v_pk_add_f32 v[90:91], v[90:91], 1.0 op_sel_hi:[1,0]
	v_cndmask_b32_e32 v168, v194, v92, vcc
	v_add_u32_e32 v92, 0xf3, v199
	v_cmp_lt_i32_e32 vcc, v92, v150
	v_log_f32_e32 v90, v90
	v_log_f32_e32 v91, v91
	v_cndmask_b32_e32 v169, v194, v93, vcc
	v_exp_f32_e64 v92, -|v168|
	v_exp_f32_e64 v93, -|v169|
	v_max_f32_e32 v166, 0, v162
	v_max_f32_e32 v167, 0, v163
	v_pk_add_f32 v[170:171], v[166:167], v[90:91]
	v_pk_add_f32 v[90:91], v[92:93], 1.0 op_sel_hi:[1,0]
	v_log_f32_e32 v92, v90
	v_max_f32_e32 v166, 0, v168
	v_add_u32_e32 v90, 0xf8, v199
	v_log_f32_e32 v93, v91
	v_cmp_lt_i32_e32 vcc, v90, v150
	v_add_u32_e32 v91, 0xf9, v199
	v_max_f32_e32 v167, 0, v169
	v_cndmask_b32_e32 v90, v194, v94, vcc
	v_cmp_lt_i32_e32 vcc, v91, v150
	v_exp_f32_e64 v94, -|v90|
	v_pk_add_f32 v[174:175], v[166:167], v[92:93]
	v_cndmask_b32_e32 v91, v194, v95, vcc
	v_exp_f32_e64 v95, -|v91|
	s_waitcnt lgkmcnt(2)
	v_mfma_f32_32x32x16_bf16 v[66:81], v[180:183], v[118:121], v[66:81]
	v_max_f32_e32 v167, 0, v91
	v_add_f32_e64 v92, v94, 1.0
	v_add_f32_e64 v93, v95, 1.0
	v_mov_b32_e32 v180, v174
	v_log_f32_e32 v94, v92
	v_max_f32_e32 v166, 0, v90
	v_add_u32_e32 v92, 0xfa, v199
	v_log_f32_e32 v95, v93
	v_cmp_lt_i32_e32 vcc, v92, v150
	v_add_u32_e32 v93, 0xfb, v199
	v_mov_b32_e32 v181, v170
	v_cndmask_b32_e32 v92, v194, v96, vcc
	v_cmp_lt_i32_e32 vcc, v93, v150
	v_exp_f32_e64 v96, -|v92|
	v_pk_add_f32 v[172:173], v[166:167], v[94:95]
	v_cndmask_b32_e32 v93, v194, v97, vcc
	v_exp_f32_e64 v97, -|v93|
	v_mov_b32_e32 v170, v175
	v_pk_add_f32 v[182:183], v[180:181], v[170:171]
	v_mov_b32_e32 v170, v171
	v_pk_add_f32 v[94:95], v[96:97], 1.0 op_sel_hi:[1,0]
	v_log_f32_e32 v94, v94
	v_log_f32_e32 v95, v95
	v_max_f32_e32 v96, 0, v92
	v_max_f32_e32 v97, 0, v93
	v_pk_add_f32 v[94:95], v[96:97], v[94:95]
	v_mov_b32_e32 v96, v160
	v_mov_b32_e32 v171, v183
	v_and_b32_e32 v160, 64, v195
	v_pk_add_f32 v[180:181], v[170:171], v[182:183] op_sel_hi:[1,0]
	v_mov_b32_e32 v170, v94
	v_mov_b32_e32 v171, v172
	v_mov_b32_e32 v172, v95
	v_xor_b32_e32 v94, 32, v195
	v_add_u32_e32 v160, 64, v160
	s_waitcnt lgkmcnt(1)
	v_mfma_f32_32x32x16_bf16 v[66:81], v[184:187], v[122:125], v[66:81]
	v_add_f32_e64 v170, v170, v172
	v_add_f32_e64 v171, v171, v173
	v_cmp_lt_i32_e32 vcc, v94, v160
	v_mov_b32_e32 v178, v164
	v_mov_b32_e32 v179, v176
	v_mov_b32_e32 v176, v165
	v_mov_b32_e32 v172, v173
	v_mov_b32_e32 v173, v171
	v_cndmask_b32_e32 v94, v195, v94, vcc
	v_mov_b32_e32 v97, v188
	v_mov_b32_e32 v188, v161
	v_pk_add_f32 v[178:179], v[178:179], v[176:177]
	v_pk_add_f32 v[172:173], v[172:173], v[170:171] op_sel_hi:[1,0]
	v_lshlrev_b32_e32 v164, 2, v94
	v_pk_add_f32 v[166:167], v[96:97], v[188:189]
	v_mov_b32_e32 v96, v189
	v_mov_b32_e32 v176, v177
	v_mov_b32_e32 v177, v179
	ds_bpermute_b32 v189, v164, v181
	ds_bpermute_b32 v188, v164, v173
	v_mov_b32_e32 v97, v167
	v_pk_add_f32 v[176:177], v[176:177], v[178:179] op_sel_hi:[1,0]
	v_pk_add_f32 v[96:97], v[96:97], v[166:167] op_sel_hi:[1,0]
	ds_bpermute_b32 v160, v164, v177
	ds_bpermute_b32 v192, v164, v97
	v_mov_b32_e32 v184, v173
	v_mov_b32_e32 v185, v181
	s_waitcnt lgkmcnt(2)
	v_pk_add_f32 v[190:191], v[184:185], v[188:189]
	v_mfma_f32_32x32x16_bf16 v[66:81], v[200:203], v[126:129], v[66:81]
	v_add_f32_e64 v186, v190, v191
	v_add_f32_e64 v187, v191, v190
	s_waitcnt lgkmcnt(1)
	v_add_f32_e32 v185, v177, v160
	v_mov_b32_e32 v184, v97
	v_mov_b32_e32 v193, v186
	s_waitcnt lgkmcnt(0)
	v_pk_add_f32 v[184:185], v[184:185], v[192:193]
	s_nop 0
	v_add_f32_e32 v94, v184, v185
	v_add_f32_e32 v94, v0, v94
	v_cmp_le_f32_e32 vcc, s49, v94
	s_cmp_eq_u64 vcc, exec
	s_cbranch_scc1 .LBB0_592
	v_add_u32_e32 v167, 0xc0, v199
	v_cmp_lt_i32_e32 vcc, v167, v150
	v_add_u32_e32 v167, 0xc1, v199
	v_add_f32_e32 v179, 0, v94
	v_cndmask_b32_e32 v66, v194, v66, vcc
	v_cmp_lt_i32_e32 vcc, v167, v150
	v_exp_f32_e64 v200, -|v66|
	v_max_f32_e32 v167, v66, v66
	v_cndmask_b32_e32 v67, v194, v67, vcc
	v_exp_f32_e64 v201, -|v67|
	v_max_f32_e32 v202, 0, v167
	v_add_u32_e32 v167, 0xc2, v199
	v_cmp_lt_i32_e32 vcc, v167, v150
	v_add_u32_e32 v167, 0xc3, v199
	v_pk_add_f32 v[200:201], v[200:201], 1.0 op_sel_hi:[1,0]
	v_cndmask_b32_e32 v68, v194, v68, vcc
	v_cmp_lt_i32_e32 vcc, v167, v150
	v_log_f32_e32 v200, v200
	v_log_f32_e32 v201, v201
	v_cndmask_b32_e32 v69, v194, v69, vcc
	v_exp_f32_e64 v204, -|v68|
	v_exp_f32_e64 v205, -|v69|
	v_max_f32_e32 v203, 0, v67
	v_pk_add_f32 v[200:201], v[202:203], v[200:201]
	v_pk_add_f32 v[202:203], v[204:205], 1.0 op_sel_hi:[1,0]
	v_max_f32_e32 v204, 0, v68
	v_add_u32_e32 v167, 0xc8, v199
	v_cmp_lt_i32_e32 vcc, v167, v150
	v_add_u32_e32 v167, 0xc9, v199
	v_log_f32_e32 v202, v202
	v_cndmask_b32_e32 v70, v194, v70, vcc
	v_cmp_lt_i32_e32 vcc, v167, v150
	v_log_f32_e32 v203, v203
	v_exp_f32_e64 v206, -|v70|
	v_cndmask_b32_e32 v71, v194, v71, vcc
	v_exp_f32_e64 v207, -|v71|
	v_max_f32_e32 v205, 0, v69
	v_pk_add_f32 v[202:203], v[204:205], v[202:203]
	v_pk_add_f32 v[204:205], v[206:207], 1.0 op_sel_hi:[1,0]
	v_max_f32_e32 v206, 0, v70
	v_add_u32_e32 v167, 0xca, v199
	v_cmp_lt_i32_e32 vcc, v167, v150
	v_add_u32_e32 v167, 0xcb, v199
	v_log_f32_e32 v204, v204
	v_cndmask_b32_e32 v72, v194, v72, vcc
	v_cmp_lt_i32_e32 vcc, v167, v150
	v_log_f32_e32 v205, v205
	v_exp_f32_e64 v208, -|v72|
	v_cndmask_b32_e32 v73, v194, v73, vcc
	v_exp_f32_e64 v209, -|v73|
	v_max_f32_e32 v207, 0, v71
	v_pk_add_f32 v[204:205], v[206:207], v[204:205]
	v_pk_add_f32 v[206:207], v[208:209], 1.0 op_sel_hi:[1,0]
	v_max_f32_e32 v208, 0, v72
	v_add_u32_e32 v167, 0xd0, v199
	v_cmp_lt_i32_e32 vcc, v167, v150
	v_add_u32_e32 v167, 0xd1, v199
	v_log_f32_e32 v206, v206
	v_cndmask_b32_e32 v74, v194, v74, vcc
	v_cmp_lt_i32_e32 vcc, v167, v150
	v_log_f32_e32 v207, v207
	v_exp_f32_e64 v210, -|v74|
	v_cndmask_b32_e32 v75, v194, v75, vcc
	v_exp_f32_e64 v211, -|v75|
	v_max_f32_e32 v209, 0, v73
	v_pk_add_f32 v[206:207], v[208:209], v[206:207]
	v_pk_add_f32 v[208:209], v[210:211], 1.0 op_sel_hi:[1,0]
	v_max_f32_e32 v210, 0, v74
	v_add_u32_e32 v167, 0xd2, v199
	v_cmp_lt_i32_e32 vcc, v167, v150
	v_add_u32_e32 v167, 0xd3, v199
	v_log_f32_e32 v208, v208
	v_cndmask_b32_e32 v76, v194, v76, vcc
	v_cmp_lt_i32_e32 vcc, v167, v150
	v_log_f32_e32 v209, v209
	v_exp_f32_e64 v212, -|v76|
	v_cndmask_b32_e32 v77, v194, v77, vcc
	v_exp_f32_e64 v213, -|v77|
	v_max_f32_e32 v211, 0, v75
	v_pk_add_f32 v[208:209], v[210:211], v[208:209]
	v_pk_add_f32 v[210:211], v[212:213], 1.0 op_sel_hi:[1,0]
	v_max_f32_e32 v212, 0, v76
	v_add_u32_e32 v167, 0xd8, v199
	v_cmp_lt_i32_e32 vcc, v167, v150
	v_add_u32_e32 v167, 0xd9, v199
	v_log_f32_e32 v210, v210
	v_cndmask_b32_e32 v78, v194, v78, vcc
	v_cmp_lt_i32_e32 vcc, v167, v150
	v_log_f32_e32 v211, v211
	v_exp_f32_e64 v214, -|v78|
	v_cndmask_b32_e32 v79, v194, v79, vcc
	v_exp_f32_e64 v215, -|v79|
	v_max_f32_e32 v213, 0, v77
	v_pk_add_f32 v[210:211], v[212:213], v[210:211]
	v_pk_add_f32 v[212:213], v[214:215], 1.0 op_sel_hi:[1,0]
	v_max_f32_e32 v214, 0, v78
	v_add_u32_e32 v167, 0xda, v199
	v_cmp_lt_i32_e32 vcc, v167, v150
	v_add_u32_e32 v167, 0xdb, v199
	v_log_f32_e32 v212, v212
	v_cndmask_b32_e32 v80, v194, v80, vcc
	v_cmp_lt_i32_e32 vcc, v167, v150
	v_log_f32_e32 v213, v213
	v_exp_f32_e64 v216, -|v80|
	v_cndmask_b32_e32 v81, v194, v81, vcc
	v_exp_f32_e64 v217, -|v81|
	v_max_f32_e32 v215, 0, v79
	v_pk_add_f32 v[212:213], v[214:215], v[212:213]
	v_pk_add_f32 v[214:215], v[216:217], 1.0 op_sel_hi:[1,0]
	v_log_f32_e32 v214, v214
	v_log_f32_e32 v215, v215
	v_max_f32_e32 v216, 0, v80
	v_max_f32_e32 v217, 0, v81
	v_pk_add_f32 v[214:215], v[216:217], v[214:215]
	v_mov_b32_e32 v220, v210
	v_mov_b32_e32 v221, v208
	v_mov_b32_e32 v208, v211
	v_mov_b32_e32 v222, v214
	v_mov_b32_e32 v223, v212
	v_mov_b32_e32 v212, v215
	v_pk_add_f32 v[220:221], v[220:221], v[208:209]
	v_pk_add_f32 v[222:223], v[222:223], v[212:213]
	v_mov_b32_e32 v208, v209
	v_mov_b32_e32 v209, v221
	v_mov_b32_e32 v212, v213
	v_mov_b32_e32 v213, v223
	v_pk_add_f32 v[208:209], v[208:209], v[220:221] op_sel_hi:[1,0]
	v_pk_add_f32 v[212:213], v[212:213], v[222:223] op_sel_hi:[1,0]
	ds_bpermute_b32 v226, v164, v209
	ds_bpermute_b32 v227, v164, v213
	v_mov_b32_e32 v216, v202
	v_mov_b32_e32 v217, v200
	v_mov_b32_e32 v200, v203
	v_mov_b32_e32 v218, v206
	v_mov_b32_e32 v219, v204
	v_mov_b32_e32 v204, v207
	v_pk_add_f32 v[216:217], v[216:217], v[200:201]
	v_pk_add_f32 v[218:219], v[218:219], v[204:205]
	v_mov_b32_e32 v200, v201
	v_mov_b32_e32 v201, v217
	v_mov_b32_e32 v204, v205
	v_mov_b32_e32 v205, v219
	v_mov_b32_e32 v221, v211
	v_mov_b32_e32 v210, v209
	v_mov_b32_e32 v211, v213
	v_pk_add_f32 v[200:201], v[200:201], v[216:217] op_sel_hi:[1,0]
	v_pk_add_f32 v[204:205], v[204:205], v[218:219] op_sel_hi:[1,0]
	s_waitcnt lgkmcnt(0)
	v_pk_add_f32 v[210:211], v[210:211], v[226:227]
	ds_bpermute_b32 v202, v164, v201
	ds_bpermute_b32 v167, v164, v205
	v_cndmask_b32_e64 v164, 0, v226, s[4:5]
	v_add_f32_e32 v184, v94, v211
	v_add_f32_e32 v164, v164, v184
	v_pk_add_f32 v[220:221], v[220:221], v[164:165] op_sel_hi:[1,0]
	s_waitcnt lgkmcnt(0)
	v_cndmask_b32_e64 v174, 0, v167, s[4:5]
	v_pk_add_f32 v[76:77], v[76:77], v[220:221] neg_lo:[0,1] neg_hi:[0,1]
	v_mov_b32_e32 v219, v207
	v_exp_f32_e32 v184, v77
	v_exp_f32_e32 v187, v76
	v_pk_add_f32 v[76:77], v[208:209], v[164:165] op_sel:[1,0] op_sel_hi:[0,0]
	v_pk_add_f32 v[74:75], v[74:75], v[76:77] neg_lo:[0,1] neg_hi:[0,1]
	v_mov_b32_e32 v217, v203
	v_exp_f32_e32 v77, v75
	v_exp_f32_e32 v164, v74
	v_pk_add_f32 v[74:75], v[210:211], v[210:211] op_sel:[0,1] op_sel_hi:[1,0]
	v_cndmask_b32_e64 v171, 0, v202, s[4:5]
	v_add_f32_e32 v75, v94, v74
	v_add_f32_e32 v76, v174, v75
	v_pk_add_f32 v[206:207], v[218:219], v[76:77] op_sel_hi:[1,0]
	v_mov_b32_e32 v203, v74
	v_pk_add_f32 v[72:73], v[72:73], v[206:207] neg_lo:[0,1] neg_hi:[0,1]
	v_cndmask_b32_e64 v183, 0, v227, s[4:5]
	v_exp_f32_e32 v174, v73
	v_exp_f32_e32 v191, v72
	v_pk_add_f32 v[72:73], v[204:205], v[76:77] op_sel:[1,0] op_sel_hi:[0,0]
	v_pk_add_f32 v[70:71], v[70:71], v[72:73] neg_lo:[0,1] neg_hi:[0,1]
	v_mov_b32_e32 v223, v215
	v_exp_f32_e32 v73, v71
	v_exp_f32_e32 v76, v70
	v_add_f32_e32 v71, v205, v167
	v_mov_b32_e32 v70, v201
	v_pk_add_f32 v[70:71], v[70:71], v[202:203]
	s_nop 0
	v_add_f32_e32 v72, v94, v71
	v_add_f32_e32 v72, v171, v72
	v_pk_add_f32 v[74:75], v[216:217], v[72:73] op_sel_hi:[1,0]
	s_nop 0
	v_pk_add_f32 v[68:69], v[68:69], v[74:75] neg_lo:[0,1] neg_hi:[0,1]
	s_nop 0
	v_exp_f32_e32 v74, v69
	v_exp_f32_e32 v75, v68
	v_pk_add_f32 v[68:69], v[200:201], v[72:73] op_sel:[1,0] op_sel_hi:[0,0]
	v_pk_add_f32 v[66:67], v[66:67], v[68:69] neg_lo:[0,1] neg_hi:[0,1]
	s_nop 0
	v_exp_f32_e32 v167, v66
	v_add_f32_e32 v66, v179, v183
	v_exp_f32_e32 v72, v67
	v_pk_add_f32 v[68:69], v[212:213], v[66:67] op_sel:[1,0] op_sel_hi:[0,0]
	v_pk_add_f32 v[66:67], v[222:223], v[66:67] op_sel_hi:[1,0]
	v_pk_add_f32 v[68:69], v[78:79], v[68:69] neg_lo:[0,1] neg_hi:[0,1]
	v_pk_add_f32 v[66:67], v[80:81], v[66:67] neg_lo:[0,1] neg_hi:[0,1]
	v_exp_f32_e32 v68, v68
	v_exp_f32_e32 v69, v69
	v_exp_f32_e32 v78, v66
	v_exp_f32_e32 v79, v67
	v_add_f32_e32 v66, v70, v71
	v_add_f32_e32 v94, v94, v66
	v_cvt_pk_bf16_f32 v70, v167, v72
	v_cvt_pk_bf16_f32 v71, v75, v74
	v_cvt_pk_bf16_f32 v72, v76, v73
	v_cvt_pk_bf16_f32 v73, v191, v174
	v_cvt_pk_bf16_f32 v66, v164, v77
	v_cvt_pk_bf16_f32 v67, v187, v184
	v_cvt_pk_bf16_f32 v68, v68, v69
	v_cvt_pk_bf16_f32 v69, v78, v79
	s_branch .LBB0_593
